# instruction trims in the three attention tile loops: MFMA C=0 instead of 32 broadcast movs, permlane32 row-max exchange, dead index math removed
# speedup vs baseline: 1.0104x; 1.0102x over previous
.LBB0_634:
	s_lshl_b32 s0, 1, s0
	s_waitcnt vmcnt(1)
	v_and_b32_e32 v0, s0, v187
	v_mov_b32_e32 v167, 0
	v_cmp_ne_u32_e64 s[6:7], 0, v0
	v_cmp_le_u32_e32 vcc, s85, v143
	v_mov_b32_e32 v0, 0
	s_and_saveexec_b64 s[2:3], vcc
	v_cndmask_b32_e64 v0, 0, 1, s[6:7]
	v_cmp_ne_u32_e32 vcc, 0, v0
	s_cmp_lg_u64 vcc, 0
	s_cselect_b64 s[4:5], -1, 0
	v_cndmask_b32_e64 v0, 0, 1, s[4:5]
	s_or_b64 exec, exec, s[2:3]
	s_waitcnt vmcnt(0)
	v_and_b32_e32 v66, s0, v188
	v_cmp_ne_u32_e32 vcc, 0, v66
	v_cmp_le_u32_e64 s[2:3], s85, v177
	s_and_saveexec_b64 s[4:5], s[2:3]
	v_cndmask_b32_e64 v66, 0, 1, vcc
	v_cmp_ne_u32_e64 s[2:3], 0, v66
	s_cmp_lg_u64 s[2:3], 0
	s_cselect_b64 s[0:1], -1, 0
	v_cndmask_b32_e64 v167, 0, 1, s[0:1]
	s_or_b64 exec, exec, s[4:5]
	v_and_b32_e32 v66, 1, v0
	v_cmp_eq_u32_e64 s[8:9], 1, v66
	v_and_b32_e32 v66, 1, v167
	v_cmp_eq_u32_e64 s[2:3], 1, v66
	s_or_b64 s[0:1], s[8:9], s[2:3]
	s_and_saveexec_b64 s[54:55], s[0:1]
	s_cbranch_execz .LBB0_646
	s_cmp_eq_u32 s87, 0
	s_cselect_b64 s[58:59], -1, 0
	s_and_b64 s[0:1], s[58:59], exec
	s_cselect_b32 s0, 0, 0x2400
	v_add_u32_e32 v168, s0, v178
	ds_read_b128 v[158:161], v168
	ds_read_b128 v[162:165], v176 offset:53248
	v_cmp_gt_i32_e64 s[4:5], s85, v190
	s_waitcnt lgkmcnt(2)
	v_cndmask_b32_e64 v66, v173, v189, s[6:7]
	ds_read_b128 v[196:199], v168 offset:32
	ds_read_b128 v[202:205], v176 offset:54272
	ds_read_b128 v[206:209], v176 offset:57344
	ds_read_b128 v[210:213], v176 offset:58368
	v_cndmask_b32_e64 v166, 0, v171, s[4:5]
	v_cndmask_b32_e64 v66, v66, 0, s[4:5]
	v_cndmask_b32_e32 v67, v173, v189, vcc
	v_cmp_gt_i32_e64 s[4:5], s85, v191
	v_cndmask_b32_e64 v240, v173, v66, s[8:9]
	s_nop 0
	v_cndmask_b32_e64 v67, v67, 0, s[4:5]
	s_nop 1
	v_cndmask_b32_e64 v241, v173, v67, s[2:3]
	s_waitcnt lgkmcnt(4)
	v_mfma_f32_32x32x16_bf16 v[98:113], v[158:161], v[162:165], 0
	s_waitcnt lgkmcnt(1)
	v_mfma_f32_32x32x16_bf16 v[114:129], v[158:161], v[206:209], 0
	ds_read_b128 v[158:161], v168 offset:4608
	ds_read_b128 v[214:217], v168 offset:4640
	s_waitcnt lgkmcnt(1)
	v_mfma_f32_32x32x16_bf16 v[82:97], v[158:161], v[162:165], 0
	v_mfma_f32_32x32x16_bf16 v[66:81], v[158:161], v[206:209], 0
	v_mfma_f32_32x32x16_bf16 v[98:113], v[196:199], v[202:205], v[98:113]
	v_mfma_f32_32x32x16_bf16 v[114:129], v[196:199], v[210:213], v[114:129]
	ds_read_b128 v[158:161], v168 offset:64
	ds_read_b128 v[162:165], v176 offset:55296
	ds_read_b128 v[196:199], v168 offset:96
	ds_read_b128 v[206:209], v176 offset:56320
	s_waitcnt lgkmcnt(4)
	v_mfma_f32_32x32x16_bf16 v[82:97], v[214:217], v[202:205], v[82:97]
	v_mfma_f32_32x32x16_bf16 v[66:81], v[214:217], v[210:213], v[66:81]
	ds_read_b128 v[202:205], v176 offset:59392
	ds_read_b128 v[210:213], v176 offset:60416
	s_waitcnt lgkmcnt(4)
	v_mfma_f32_32x32x16_bf16 v[98:113], v[158:161], v[162:165], v[98:113]
	s_waitcnt lgkmcnt(1)
	v_mfma_f32_32x32x16_bf16 v[114:129], v[158:161], v[202:205], v[114:129]
	ds_read_b128 v[158:161], v168 offset:4672
	ds_read_b128 v[214:217], v168 offset:4704
	s_waitcnt lgkmcnt(1)
	v_mfma_f32_32x32x16_bf16 v[82:97], v[158:161], v[162:165], v[82:97]
	v_mfma_f32_32x32x16_bf16 v[66:81], v[158:161], v[202:205], v[66:81]
	v_cndmask_b32_e64 v158, 0, v172, s[6:7]
	v_or3_b32 v0, v158, v166, v0
	v_cndmask_b32_e64 v158, v158, v0, s[8:9]
	v_and_b32_e32 v0, 0x100, v158
	v_cmp_ne_u32_e64 s[6:7], 0, v0
	v_add_u32_e32 v0, s60, v192
	v_mfma_f32_32x32x16_bf16 v[98:113], v[196:199], v[206:209], v[98:113]
	v_mfma_f32_32x32x16_bf16 v[114:129], v[196:199], v[210:213], v[114:129]
	s_waitcnt lgkmcnt(0)
	v_mfma_f32_32x32x16_bf16 v[82:97], v[214:217], v[206:209], v[82:97]
	v_mfma_f32_32x32x16_bf16 v[66:81], v[214:217], v[210:213], v[66:81]
	s_and_saveexec_b64 s[8:9], s[6:7]
	s_cbranch_execz .LBB0_641
	v_lshl_add_u32 v206, v0, 2, s92
	v_and_b32_e32 v205, 0x10000, v158
	v_cmp_ne_u32_e64 s[6:7], 0, v205
	v_mov_b32_e32 v207, s93
	s_nop 1
	v_cndmask_b32_e64 v206, v207, v206, s[6:7]
	ds_read_b32 v208, v206 offset:236
	ds_read_b32 v209, v206 offset:232
	ds_read_b32 v210, v206 offset:228
	ds_read_b32 v211, v206 offset:224
	ds_read_b32 v212, v206 offset:204
	ds_read_b32 v213, v206 offset:200
	ds_read_b32 v214, v206 offset:196
	ds_read_b32 v215, v206 offset:192
	ds_read_b32 v216, v206 offset:172
	ds_read_b32 v217, v206 offset:168
	ds_read_b32 v218, v206 offset:164
	ds_read_b32 v219, v206 offset:160
	ds_read_b32 v220, v206 offset:140
	ds_read_b32 v221, v206 offset:136
	ds_read_b32 v222, v206 offset:132
	ds_read_b32 v223, v206 offset:128
	ds_read_b32 v224, v206 offset:108
	ds_read_b32 v225, v206 offset:104
	ds_read_b32 v226, v206 offset:100
	ds_read_b32 v227, v206 offset:96
	ds_read_b32 v228, v206 offset:76
	ds_read_b32 v229, v206 offset:72
	ds_read_b32 v230, v206 offset:68
	ds_read_b32 v231, v206 offset:64
	ds_read_b32 v232, v206 offset:44
	ds_read_b32 v233, v206 offset:40
	ds_read_b32 v234, v206 offset:36
	ds_read_b32 v235, v206 offset:32
	ds_read_b32 v236, v206 offset:12
	ds_read_b32 v237, v206 offset:8
	ds_read_b32 v238, v206 offset:4
	ds_read_b32 v239, v206 offset:0
	s_waitcnt lgkmcnt(14)
	v_pk_add_f32 v[98:99], v[98:99], v[208:209]
	v_pk_add_f32 v[100:101], v[100:101], v[210:211]
	v_pk_add_f32 v[102:103], v[102:103], v[212:213]
	v_pk_add_f32 v[104:105], v[104:105], v[214:215]
	v_pk_add_f32 v[106:107], v[106:107], v[216:217]
	v_pk_add_f32 v[108:109], v[108:109], v[218:219]
	v_pk_add_f32 v[110:111], v[110:111], v[220:221]
	v_pk_add_f32 v[112:113], v[112:113], v[222:223]
	s_waitcnt lgkmcnt(0)
	v_pk_add_f32 v[82:83], v[82:83], v[224:225]
	v_pk_add_f32 v[84:85], v[84:85], v[226:227]
	v_pk_add_f32 v[86:87], v[86:87], v[228:229]
	v_pk_add_f32 v[88:89], v[88:89], v[230:231]
	v_pk_add_f32 v[90:91], v[90:91], v[232:233]
	v_pk_add_f32 v[92:93], v[92:93], v[234:235]
	v_pk_add_f32 v[94:95], v[94:95], v[236:237]
	v_pk_add_f32 v[96:97], v[96:97], v[238:239]

.LBB0_643:
	s_or_b64 exec, exec, s[2:3]
	v_max_f32_e32 v0, v98, v82
	v_max_f32_e32 v158, v99, v83
	v_max_f32_e32 v159, v101, v85
	v_max3_f32 v160, v100, v84, v104
	v_max3_f32 v159, v159, v105, v89
	v_max3_f32 v0, v0, v102, v86
	v_max3_f32 v158, v158, v103, v87
	v_max3_f32 v160, v160, v88, v108
	v_max3_f32 v159, v159, v109, v93
	v_max3_f32 v0, v0, v106, v90
	v_max3_f32 v158, v158, v107, v91
	v_max3_f32 v160, v160, v92, v112
	v_max3_f32 v159, v159, v113, v97
	v_max3_f32 v0, v0, v110, v94
	v_max3_f32 v158, v158, v111, v95
	v_max3_f32 v159, v160, v96, v159
	v_max3_f32 v0, v0, v158, v159
	v_max_f32_e32 v158, v114, v66
	v_max_f32_e32 v159, v115, v67
	v_max_f32_e32 v160, v117, v69
	v_max3_f32 v161, v116, v68, v120
	v_max3_f32 v160, v160, v121, v73
	v_max3_f32 v161, v161, v72, v124
	v_max3_f32 v160, v160, v125, v77
	v_max3_f32 v161, v161, v76, v128
	v_max3_f32 v160, v160, v129, v81
	v_max3_f32 v160, v161, v80, v160
	v_max3_f32 v158, v158, v118, v70
	v_max3_f32 v159, v159, v119, v71
	v_max3_f32 v158, v158, v122, v74
	v_max3_f32 v159, v159, v123, v75
	v_max3_f32 v158, v158, v126, v78
	v_max3_f32 v159, v159, v127, v79
	v_max3_f32 v159, v158, v159, v160
	v_mov_b32_e32 v162, v0
	v_mov_b32_e32 v160, v159
	s_nop 1
	v_permlane32_swap_b32_e32 v0, v162
	v_permlane32_swap_b32_e32 v159, v160
	v_max_f32_e32 v158, v0, v162
	v_max_f32_e32 v0, v159, v160
	v_add_f32_e32 v158, v158, v240
	v_add_f32_e32 v0, v0, v241
	v_add_f32_e32 v159, 0x42317218, v194
	v_cmp_gt_f32_e32 vcc, v158, v159
	v_add_f32_e32 v159, 0x42317218, v193
	v_cmp_gt_f32_e64 s[2:3], v0, v159
	s_or_b64 vcc, vcc, s[2:3]
	s_cbranch_vccz .LBB0_645
	v_max_f32_e32 v158, v158, v158
	v_max_f32_e32 v159, v194, v194
	v_max_f32_e32 v160, v159, v158
	v_max_f32_e32 v0, v0, v0
	v_max_f32_e32 v158, v193, v193
	v_cmp_ngt_f32_e32 vcc, s76, v160
	v_max_f32_e32 v161, v158, v0
	s_nop 0
	v_cndmask_b32_e32 v0, 0, v160, vcc
	v_sub_f32_e32 v0, v194, v0
	v_mul_f32_e32 v0, 0x3e38aa3b, v0
	v_cmp_ngt_f32_e32 vcc, s76, v161
	v_exp_f32_e32 v159, v0
	v_mov_b32_e32 v194, v160
	v_cndmask_b32_e32 v0, 0, v161, vcc
	v_sub_f32_e32 v0, v193, v0
	v_mul_f32_e32 v0, 0x3e38aa3b, v0
	v_exp_f32_e32 v158, v0
	v_mov_b32_e32 v0, v159
	v_pk_mul_f32 v[64:65], v[64:65], v[0:1] op_sel_hi:[1,0]
	v_pk_mul_f32 v[62:63], v[62:63], v[0:1] op_sel_hi:[1,0]
	v_pk_mul_f32 v[156:157], v[156:157], v[158:159]
	v_pk_mul_f32 v[60:61], v[60:61], v[0:1] op_sel_hi:[1,0]
	v_pk_mul_f32 v[58:59], v[58:59], v[0:1] op_sel_hi:[1,0]
	v_pk_mul_f32 v[56:57], v[56:57], v[0:1] op_sel_hi:[1,0]
	v_pk_mul_f32 v[54:55], v[54:55], v[0:1] op_sel_hi:[1,0]
	v_pk_mul_f32 v[52:53], v[52:53], v[0:1] op_sel_hi:[1,0]
	v_pk_mul_f32 v[50:51], v[50:51], v[0:1] op_sel_hi:[1,0]
	v_pk_mul_f32 v[16:17], v[16:17], v[158:159] op_sel_hi:[1,0]
	v_pk_mul_f32 v[14:15], v[14:15], v[158:159] op_sel_hi:[1,0]
	v_pk_mul_f32 v[12:13], v[12:13], v[158:159] op_sel_hi:[1,0]
	v_pk_mul_f32 v[10:11], v[10:11], v[158:159] op_sel_hi:[1,0]
	v_pk_mul_f32 v[8:9], v[8:9], v[158:159] op_sel_hi:[1,0]
	v_pk_mul_f32 v[6:7], v[6:7], v[158:159] op_sel_hi:[1,0]
	v_pk_mul_f32 v[4:5], v[4:5], v[158:159] op_sel_hi:[1,0]
	v_pk_mul_f32 v[2:3], v[2:3], v[158:159] op_sel_hi:[1,0]
	v_pk_mul_f32 v[48:49], v[48:49], v[0:1] op_sel_hi:[1,0]
	v_pk_mul_f32 v[46:47], v[46:47], v[0:1] op_sel_hi:[1,0]
	v_pk_mul_f32 v[44:45], v[44:45], v[0:1] op_sel_hi:[1,0]
	v_pk_mul_f32 v[42:43], v[42:43], v[0:1] op_sel_hi:[1,0]
	v_pk_mul_f32 v[40:41], v[40:41], v[0:1] op_sel_hi:[1,0]
	v_pk_mul_f32 v[38:39], v[38:39], v[0:1] op_sel_hi:[1,0]
	v_pk_mul_f32 v[36:37], v[36:37], v[0:1] op_sel_hi:[1,0]
	v_pk_mul_f32 v[34:35], v[34:35], v[0:1] op_sel_hi:[1,0]
	v_pk_mul_f32 v[32:33], v[32:33], v[158:159] op_sel_hi:[1,0]
	v_pk_mul_f32 v[30:31], v[30:31], v[158:159] op_sel_hi:[1,0]
	v_pk_mul_f32 v[28:29], v[28:29], v[158:159] op_sel_hi:[1,0]
	v_pk_mul_f32 v[26:27], v[26:27], v[158:159] op_sel_hi:[1,0]
	v_pk_mul_f32 v[24:25], v[24:25], v[158:159] op_sel_hi:[1,0]
	v_pk_mul_f32 v[22:23], v[22:23], v[158:159] op_sel_hi:[1,0]
	v_pk_mul_f32 v[20:21], v[20:21], v[158:159] op_sel_hi:[1,0]
	v_pk_mul_f32 v[18:19], v[18:19], v[158:159] op_sel_hi:[1,0]
	v_mov_b32_e32 v193, v161
.LBB0_645:
	v_mul_f32_e32 v0, 0x3e38aa3b, v194
	v_cmp_ngt_f32_e32 vcc, s76, v194
	v_mul_f32_e32 v158, 0x3e38aa3b, v193
	s_and_b64 s[0:1], s[58:59], exec
	v_cndmask_b32_e32 v0, 0, v0, vcc
	v_fma_f32 v0, -v240, s77, v0
	v_cmp_ngt_f32_e32 vcc, s76, v193
	v_fma_f32 v98, v98, s77, -v0
	v_exp_f32_e32 v159, v98
	v_cndmask_b32_e32 v195, 0, v158, vcc
	v_fma_f32 v195, -v241, s77, v195
	v_fma_f32 v66, v66, s77, -v195
	v_exp_f32_e32 v158, v66
	v_fma_f32 v66, v99, s77, -v0
	v_exp_f32_e32 v99, v66
	v_fma_f32 v66, v115, s77, -v195
	v_fma_f32 v98, v114, s77, -v195
	v_exp_f32_e32 v114, v66
	v_fma_f32 v66, v83, s77, -v0
	v_exp_f32_e32 v115, v66
	v_fma_f32 v66, v67, s77, -v195
	v_exp_f32_e32 v160, v98
	v_exp_f32_e32 v98, v66
	v_fma_f32 v66, v100, s77, -v0
	v_exp_f32_e32 v67, v66
	v_fma_f32 v66, v116, s77, -v195
	v_exp_f32_e32 v162, v66
	v_fma_f32 v66, v84, s77, -v0
	v_exp_f32_e32 v163, v66
	v_fma_f32 v66, v68, s77, -v195
	v_fma_f32 v68, v101, s77, -v0
	v_exp_f32_e32 v83, v68
	v_fma_f32 v68, v117, s77, -v195
	v_exp_f32_e32 v100, v68
	v_fma_f32 v68, v85, s77, -v0
	v_fma_f32 v82, v82, s77, -v0
	v_exp_f32_e32 v101, v68
	v_fma_f32 v68, v69, s77, -v195
	v_exp_f32_e32 v161, v82
	v_exp_f32_e32 v82, v68
	v_fma_f32 v68, v102, s77, -v0
	v_exp_f32_e32 v69, v68
	v_fma_f32 v68, v118, s77, -v195
	v_exp_f32_e32 v116, v68
	v_fma_f32 v68, v86, s77, -v0
	v_exp_f32_e32 v117, v68
	v_fma_f32 v68, v70, s77, -v195
	v_fma_f32 v70, v103, s77, -v0
	v_exp_f32_e32 v85, v70
	v_fma_f32 v70, v119, s77, -v195
	v_exp_f32_e32 v164, v70
	v_fma_f32 v70, v87, s77, -v0
	v_pk_add_f32 v[86:87], v[160:161], 0 op_sel_hi:[1,0]
	v_exp_f32_e32 v165, v70
	v_fma_f32 v70, v71, s77, -v195
	v_pk_add_f32 v[86:87], v[114:115], v[86:87]
	v_exp_f32_e32 v84, v70
	v_fma_f32 v70, v104, s77, -v0
	v_pk_add_f32 v[86:87], v[162:163], v[86:87]
	v_exp_f32_e32 v71, v70
	v_fma_f32 v70, v120, s77, -v195
	v_pk_add_f32 v[86:87], v[100:101], v[86:87]
	v_exp_f32_e32 v166, v70
	v_fma_f32 v70, v88, s77, -v0
	v_pk_add_f32 v[86:87], v[116:117], v[86:87]
	v_exp_f32_e32 v167, v70
	v_fma_f32 v70, v72, s77, -v195
	v_pk_add_f32 v[168:169], v[164:165], v[86:87]
	v_fma_f32 v72, v105, s77, -v0
	v_fma_f32 v86, v107, s77, -v0
	v_exp_f32_e32 v87, v72
	v_fma_f32 v72, v121, s77, -v195
	v_exp_f32_e32 v105, v86
	v_fma_f32 v86, v123, s77, -v195
	v_exp_f32_e32 v88, v72
	v_fma_f32 v72, v106, s77, -v0
	v_exp_f32_e32 v106, v86
	v_fma_f32 v86, v108, s77, -v0
	v_exp_f32_e32 v119, v86
	v_fma_f32 v86, v124, s77, -v195
	s_cselect_b32 s0, s78, 0x7800
	v_exp_f32_e32 v108, v86
	v_fma_f32 v86, v109, s77, -v0
	v_add_u32_e32 v201, s0, v179
	v_exp_f32_e32 v211, v86
	v_fma_f32 v86, v125, s77, -v195
	v_exp_f32_e32 v103, v72
	v_fma_f32 v72, v122, s77, -v195
	v_cvt_pk_bf16_f32 v120, v159, v99
	v_cvt_pk_bf16_f32 v121, v67, v83
	v_cvt_pk_bf16_f32 v122, v69, v85
	v_cvt_pk_bf16_f32 v123, v71, v87
	v_cvt_pk_bf16_f32 v196, v160, v114
	v_cvt_pk_bf16_f32 v197, v162, v100
	v_cvt_pk_bf16_f32 v198, v116, v164
	v_cvt_pk_bf16_f32 v199, v166, v88
	ds_read_b64_tr_b16 v[202:203], v201
	ds_read_b64_tr_b16 v[204:205], v201 offset:1536
	v_exp_f32_e32 v100, v86
	v_fma_f32 v86, v110, s77, -v0
	ds_read_b64_tr_b16 v[208:209], v201 offset:1600
	ds_read_b64_tr_b16 v[206:207], v201 offset:64
	v_exp_f32_e32 v213, v86
	v_fma_f32 v86, v126, s77, -v195
	v_exp_f32_e32 v160, v86
	v_fma_f32 v86, v111, s77, -v0
	v_exp_f32_e32 v215, v86
	v_fma_f32 v86, v127, s77, -v195
	v_exp_f32_e32 v162, v86
	v_fma_f32 v86, v112, s77, -v0
	s_waitcnt lgkmcnt(2)
	v_mfma_f32_32x32x16_bf16 v[50:65], v[202:205], v[120:123], v[50:65]
	v_exp_f32_e32 v72, v72
	v_cvt_pk_bf16_f32 v110, v103, v105
	v_cvt_pk_bf16_f32 v111, v119, v211
	v_cvt_pk_bf16_f32 v112, v213, v215
	v_fma_f32 v74, v74, s77, -v195
	v_exp_f32_e32 v102, v74
	v_fma_f32 v74, v91, s77, -v0
	v_mfma_f32_32x32x16_bf16 v[2:17], v[202:205], v[196:199], v[2:17]
	v_exp_f32_e32 v203, v86
	v_fma_f32 v86, v128, s77, -v195
	v_exp_f32_e32 v128, v86
	v_fma_f32 v86, v113, s77, -v0
	v_exp_f32_e32 v205, v86
	v_fma_f32 v86, v129, s77, -v195
	v_exp_f32_e32 v164, v86
	s_waitcnt lgkmcnt(0)
	v_mfma_f32_32x32x16_bf16 v[34:49], v[206:209], v[120:123], v[34:49]
	v_cvt_pk_bf16_f32 v113, v203, v205
	v_cvt_pk_bf16_f32 v120, v72, v106
	v_cvt_pk_bf16_f32 v121, v108, v100
	v_cvt_pk_bf16_f32 v122, v160, v162
	v_cvt_pk_bf16_f32 v123, v128, v164
	ds_read_b64_tr_b16 v[124:125], v201 offset:3072
	ds_read_b64_tr_b16 v[126:127], v201 offset:4608
	v_exp_f32_e32 v107, v74
	v_mfma_f32_32x32x16_bf16 v[18:33], v[206:209], v[196:199], v[18:33]
	ds_read_b64_tr_b16 v[198:199], v201 offset:4672
	ds_read_b64_tr_b16 v[196:197], v201 offset:3136
	v_fma_f32 v74, v75, s77, -v195
	v_exp_f32_e32 v104, v74
	v_fma_f32 v74, v92, s77, -v0
	v_exp_f32_e32 v109, v74
	v_fma_f32 v74, v76, s77, -v195
	v_fma_f32 v86, v89, s77, -v0
	v_fma_f32 v73, v73, s77, -v195
	v_exp_f32_e32 v118, v74
	v_fma_f32 v74, v93, s77, -v0
	s_waitcnt lgkmcnt(0)
	v_mfma_f32_32x32x16_bf16 v[34:49], v[196:199], v[110:113], v[34:49]
	v_exp_f32_e32 v89, v86
	v_exp_f32_e32 v86, v73
	v_fma_f32 v73, v90, s77, -v0
	v_cvt_pk_bf16_f32 v90, v161, v115
	v_cvt_pk_bf16_f32 v91, v163, v101
	v_exp_f32_e32 v101, v74
	v_fma_f32 v74, v77, s77, -v195
	v_mfma_f32_32x32x16_bf16 v[18:33], v[196:199], v[120:123], v[18:33]
	v_exp_f32_e32 v210, v74
	v_fma_f32 v74, v94, s77, -v0
	v_exp_f32_e32 v66, v66
	v_exp_f32_e32 v68, v68
	v_exp_f32_e32 v70, v70
	v_cvt_pk_bf16_f32 v92, v117, v165
	v_cvt_pk_bf16_f32 v93, v167, v89
	v_mfma_f32_32x32x16_bf16 v[50:65], v[124:127], v[110:113], v[50:65]
	v_cvt_pk_bf16_f32 v110, v158, v98
	v_cvt_pk_bf16_f32 v111, v66, v82
	v_cvt_pk_bf16_f32 v112, v68, v84
	v_cvt_pk_bf16_f32 v113, v70, v86
	ds_read_b64_tr_b16 v[114:115], v201 offset:6144
	ds_read_b64_tr_b16 v[116:117], v201 offset:7680
	v_exp_f32_e32 v161, v74
	ds_read_b64_tr_b16 v[76:77], v201 offset:7744
	ds_read_b64_tr_b16 v[74:75], v201 offset:6208
	v_mfma_f32_32x32x16_bf16 v[2:17], v[124:127], v[120:123], v[2:17]
	v_add_f32_e64 v206, v158, 0
	v_add_f32_e64 v207, v159, 0
	v_fma_f32 v78, v78, s77, -v195
	v_exp_f32_e32 v212, v78
	v_fma_f32 v78, v95, s77, -v0
	v_exp_f32_e32 v163, v78
	v_fma_f32 v78, v79, s77, -v195
	v_exp_f32_e32 v214, v78
	s_waitcnt lgkmcnt(0)
	v_mfma_f32_32x32x16_bf16 v[34:49], v[74:77], v[90:93], v[34:49]
	v_fma_f32 v78, v96, s77, -v0
	v_fma_f32 v0, v97, s77, -v0
	v_exp_f32_e32 v73, v73
	v_exp_f32_e32 v129, v78
	v_fma_f32 v78, v80, s77, -v195
	v_exp_f32_e32 v165, v0
	v_fma_f32 v0, v81, s77, -v195
	v_mfma_f32_32x32x16_bf16 v[18:33], v[74:77], v[110:113], v[18:33]
	v_add_f32_e64 v74, v98, v206
	v_add_f32_e64 v75, v99, v207
	v_exp_f32_e32 v202, v78
	v_pk_add_f32 v[66:67], v[66:67], v[74:75]
	v_exp_f32_e32 v204, v0
	v_pk_add_f32 v[66:67], v[82:83], v[66:67]
	v_cvt_pk_bf16_f32 v78, v73, v107
	v_cvt_pk_bf16_f32 v79, v109, v101
	v_mfma_f32_32x32x16_bf16 v[50:65], v[114:117], v[90:93], v[50:65]
	v_add_f32_e64 v66, v68, v66
	v_add_f32_e64 v67, v69, v67
	v_cvt_pk_bf16_f32 v80, v161, v163
	v_cvt_pk_bf16_f32 v81, v129, v165
	v_cvt_pk_bf16_f32 v90, v102, v104
	v_cvt_pk_bf16_f32 v91, v118, v210
	v_cvt_pk_bf16_f32 v92, v212, v214
	v_cvt_pk_bf16_f32 v93, v202, v204
	v_mfma_f32_32x32x16_bf16 v[2:17], v[114:117], v[110:113], v[2:17]
	ds_read_b64_tr_b16 v[94:95], v201 offset:9216
	ds_read_b64_tr_b16 v[96:97], v201 offset:10752
	v_add_f32_e64 v74, v84, v66
	v_add_f32_e64 v75, v85, v67
	ds_read_b64_tr_b16 v[68:69], v201 offset:10816
	ds_read_b64_tr_b16 v[66:67], v201 offset:9280
	v_pk_add_f32 v[168:169], v[166:167], v[168:169]
	v_pk_add_f32 v[70:71], v[70:71], v[74:75]
	v_pk_add_f32 v[74:75], v[88:89], v[168:169]
	v_pk_add_f32 v[70:71], v[86:87], v[70:71]
	v_pk_add_f32 v[72:73], v[72:73], v[74:75]
	v_pk_add_f32 v[70:71], v[102:103], v[70:71]
	v_pk_add_f32 v[72:73], v[106:107], v[72:73]
	v_pk_add_f32 v[70:71], v[104:105], v[70:71]
	s_waitcnt lgkmcnt(2)
	v_mfma_f32_32x32x16_bf16 v[50:65], v[94:97], v[78:81], v[50:65]
	v_add_f32_e64 v72, v108, v72
	v_add_f32_e64 v73, v109, v73
	v_add_f32_e64 v70, v118, v70
	v_add_f32_e64 v71, v119, v71
	v_add_f32_e64 v72, v100, v72
	v_add_f32_e64 v73, v101, v73
	v_pk_add_f32 v[70:71], v[210:211], v[70:71]
	v_pk_add_f32 v[72:73], v[160:161], v[72:73]
	v_pk_add_f32 v[70:71], v[212:213], v[70:71]
	v_pk_add_f32 v[72:73], v[162:163], v[72:73]
	v_mfma_f32_32x32x16_bf16 v[2:17], v[94:97], v[90:93], v[2:17]
	v_add_f32_e64 v70, v214, v70
	v_add_f32_e64 v71, v215, v71
	v_add_f32_e64 v72, v128, v72
	v_add_f32_e64 v73, v129, v73
	v_add_f32_e64 v70, v202, v70
	v_add_f32_e64 v71, v203, v71
	v_pk_add_f32 v[72:73], v[164:165], v[72:73]
	v_pk_add_f32 v[70:71], v[204:205], v[70:71]
	s_nop 0
	v_pk_add_f32 v[70:71], v[72:73], v[70:71]
	s_waitcnt lgkmcnt(0)
	v_mfma_f32_32x32x16_bf16 v[34:49], v[66:69], v[78:81], v[34:49]
	v_add_f32_e64 v156, v156, v70
	v_add_f32_e64 v157, v157, v71
	v_mfma_f32_32x32x16_bf16 v[18:33], v[66:69], v[90:93], v[18:33]

.LBB0_655:
	s_add_i32 s0, s84, 63
	v_cmp_le_u32_e32 vcc, s84, v143
	v_cmp_ge_i32_e64 s[2:3], s0, v168
	s_and_b64 s[2:3], vcc, s[2:3]
	v_cmp_le_u32_e32 vcc, s84, v177
	v_cmp_ge_i32_e64 s[4:5], s0, v169
	s_and_b64 vcc, vcc, s[4:5]
	s_or_b64 s[4:5], s[2:3], vcc
	s_and_saveexec_b64 s[60:61], s[4:5]
	s_cbranch_execz .LBB0_663
	v_cmp_gt_i32_e64 s[4:5], s0, v182
	v_cmp_lt_i32_e64 s[6:7], s84, v183
	v_cmp_gt_i32_e64 s[8:9], s0, v167
	v_cmp_lt_i32_e64 s[10:11], s84, v185
	s_or_b64 s[6:7], s[4:5], s[6:7]
	s_or_b64 s[8:9], s[8:9], s[10:11]
	s_cmp_eq_u32 s86, 0
	s_cselect_b64 s[4:5], -1, 0
	s_and_b64 s[0:1], s[4:5], exec
	s_waitcnt lgkmcnt(0)
	v_cndmask_b32_e64 v0, v184, 0, s[6:7]
	v_cndmask_b32_e64 v66, v184, 0, s[8:9]
	s_cselect_b32 s0, 0, 0x2400
	v_cndmask_b32_e64 v244, v173, v66, s[2:3]
	v_cndmask_b32_e32 v245, v173, v0, vcc
	v_add_u32_e32 v0, s0, v178
	ds_read_b128 v[156:159], v0
	ds_read_b128 v[160:163], v176 offset:53248
	ds_read_b128 v[188:191], v0 offset:32
	ds_read_b128 v[192:195], v176 offset:54272
	ds_read_b128 v[196:199], v176 offset:57344
	ds_read_b128 v[202:205], v176 offset:58368
	s_waitcnt lgkmcnt(4)
	v_mfma_f32_32x32x16_bf16 v[98:113], v[156:159], v[160:163], 0
	s_and_b64 s[0:1], s[2:3], s[8:9]
	s_waitcnt lgkmcnt(1)
	v_mfma_f32_32x32x16_bf16 v[114:129], v[156:159], v[196:199], 0
	ds_read_b128 v[156:159], v0 offset:4608
	ds_read_b128 v[206:209], v0 offset:4640
	s_waitcnt lgkmcnt(1)
	v_mfma_f32_32x32x16_bf16 v[82:97], v[156:159], v[160:163], 0
	v_mfma_f32_32x32x16_bf16 v[66:81], v[156:159], v[196:199], 0
	ds_read_b128 v[156:159], v0 offset:64
	ds_read_b128 v[160:163], v176 offset:55296
	ds_read_b128 v[212:215], v0 offset:96
	ds_read_b128 v[216:219], v176 offset:56320
	v_mfma_f32_32x32x16_bf16 v[98:113], v[188:191], v[192:195], v[98:113]
	v_mfma_f32_32x32x16_bf16 v[114:129], v[188:191], v[202:205], v[114:129]
	ds_read_b128 v[188:191], v176 offset:59392
	ds_read_b128 v[220:223], v176 offset:60416
	s_waitcnt lgkmcnt(6)
	v_mfma_f32_32x32x16_bf16 v[82:97], v[206:209], v[192:195], v[82:97]
	v_mfma_f32_32x32x16_bf16 v[66:81], v[206:209], v[202:205], v[66:81]
	s_waitcnt lgkmcnt(4)
	v_mfma_f32_32x32x16_bf16 v[98:113], v[156:159], v[160:163], v[98:113]
	s_waitcnt lgkmcnt(1)
	v_mfma_f32_32x32x16_bf16 v[114:129], v[156:159], v[188:191], v[114:129]
	ds_read_b128 v[156:159], v0 offset:4672
	ds_read_b128 v[224:227], v0 offset:4704
	s_waitcnt lgkmcnt(1)
	v_mfma_f32_32x32x16_bf16 v[82:97], v[156:159], v[160:163], v[82:97]
	v_mfma_f32_32x32x16_bf16 v[66:81], v[156:159], v[188:191], v[66:81]
	v_mfma_f32_32x32x16_bf16 v[98:113], v[212:215], v[216:219], v[98:113]
	v_mfma_f32_32x32x16_bf16 v[114:129], v[212:215], v[220:223], v[114:129]
	s_waitcnt lgkmcnt(0)
	v_mfma_f32_32x32x16_bf16 v[82:97], v[224:227], v[216:219], v[82:97]
	v_mfma_f32_32x32x16_bf16 v[66:81], v[224:227], v[220:223], v[66:81]
	s_and_saveexec_b64 s[8:9], s[0:1]
	s_cbranch_execz .LBB0_658
	v_lshl_add_u32 v211, v181, 2, s95
	ds_read_b32 v212, v211 offset:236
	ds_read_b32 v213, v211 offset:232
	ds_read_b32 v214, v211 offset:228
	ds_read_b32 v215, v211 offset:224
	ds_read_b32 v216, v211 offset:204
	ds_read_b32 v217, v211 offset:200
	ds_read_b32 v218, v211 offset:196
	ds_read_b32 v219, v211 offset:192
	ds_read_b32 v220, v211 offset:172
	ds_read_b32 v221, v211 offset:168
	ds_read_b32 v222, v211 offset:164
	ds_read_b32 v223, v211 offset:160
	ds_read_b32 v224, v211 offset:140
	ds_read_b32 v225, v211 offset:136
	ds_read_b32 v226, v211 offset:132
	ds_read_b32 v227, v211 offset:128
	ds_read_b32 v228, v211 offset:108
	ds_read_b32 v229, v211 offset:104
	ds_read_b32 v230, v211 offset:100
	ds_read_b32 v231, v211 offset:96
	ds_read_b32 v232, v211 offset:76
	ds_read_b32 v233, v211 offset:72
	ds_read_b32 v234, v211 offset:68
	ds_read_b32 v235, v211 offset:64
	ds_read_b32 v236, v211 offset:44
	ds_read_b32 v237, v211 offset:40
	ds_read_b32 v238, v211 offset:36
	ds_read_b32 v239, v211 offset:32
	ds_read_b32 v240, v211 offset:12
	ds_read_b32 v241, v211 offset:8
	ds_read_b32 v242, v211 offset:4
	ds_read_b32 v243, v211 offset:0
	s_waitcnt lgkmcnt(14)
	v_pk_add_f32 v[98:99], v[98:99], v[212:213]
	v_pk_add_f32 v[100:101], v[100:101], v[214:215]
	v_pk_add_f32 v[102:103], v[102:103], v[216:217]
	v_pk_add_f32 v[104:105], v[104:105], v[218:219]
	v_pk_add_f32 v[106:107], v[106:107], v[220:221]
	v_pk_add_f32 v[108:109], v[108:109], v[222:223]
	v_pk_add_f32 v[110:111], v[110:111], v[224:225]
	v_pk_add_f32 v[112:113], v[112:113], v[226:227]
	s_waitcnt lgkmcnt(0)
	v_pk_add_f32 v[82:83], v[82:83], v[228:229]
	v_pk_add_f32 v[84:85], v[84:85], v[230:231]
	v_pk_add_f32 v[86:87], v[86:87], v[232:233]
	v_pk_add_f32 v[88:89], v[88:89], v[234:235]
	v_pk_add_f32 v[90:91], v[90:91], v[236:237]
	v_pk_add_f32 v[92:93], v[92:93], v[238:239]
	v_pk_add_f32 v[94:95], v[94:95], v[240:241]
	v_pk_add_f32 v[96:97], v[96:97], v[242:243]

.LBB0_660:
	s_or_b64 exec, exec, s[2:3]
	s_nop 3
	v_max_f32_e32 v0, v98, v82
	v_max_f32_e32 v156, v99, v83
	v_max_f32_e32 v157, v101, v85
	v_max3_f32 v158, v100, v84, v104
	v_max3_f32 v157, v157, v105, v89
	v_max3_f32 v0, v0, v102, v86
	v_max3_f32 v156, v156, v103, v87
	v_max3_f32 v158, v158, v88, v108
	v_max3_f32 v157, v157, v109, v93
	v_max3_f32 v0, v0, v106, v90
	v_max3_f32 v156, v156, v107, v91
	v_max3_f32 v158, v158, v92, v112
	v_max3_f32 v157, v157, v113, v97
	v_max3_f32 v0, v0, v110, v94
	v_max3_f32 v156, v156, v111, v95
	v_max3_f32 v157, v158, v96, v157
	v_max3_f32 v0, v0, v156, v157
	v_max_f32_e32 v156, v114, v66
	v_max_f32_e32 v157, v115, v67
	v_max_f32_e32 v158, v117, v69
	v_max3_f32 v159, v116, v68, v120
	v_max3_f32 v158, v158, v121, v73
	v_max3_f32 v156, v156, v118, v70
	v_max3_f32 v157, v157, v119, v71
	v_max3_f32 v159, v159, v72, v124
	v_max3_f32 v158, v158, v125, v77
	v_max3_f32 v156, v156, v122, v74
	v_max3_f32 v157, v157, v123, v75
	v_max3_f32 v159, v159, v76, v128
	v_max3_f32 v158, v158, v129, v81
	v_max3_f32 v156, v156, v126, v78
	v_max3_f32 v157, v157, v127, v79
	v_max3_f32 v158, v159, v80, v158
	v_max3_f32 v157, v156, v157, v158
	v_mov_b32_e32 v159, v0
	v_mov_b32_e32 v158, v157
	s_nop 1
	v_permlane32_swap_b32_e32 v0, v159
	v_permlane32_swap_b32_e32 v157, v158
	v_max_f32_e32 v156, v0, v159
	v_max_f32_e32 v0, v157, v158
	v_add_f32_e32 v156, v156, v244
	v_add_f32_e32 v0, v0, v245
	v_add_f32_e32 v157, 0x42317218, v187
	v_cmp_gt_f32_e32 vcc, v156, v157
	v_add_f32_e32 v157, 0x42317218, v186
	v_cmp_gt_f32_e64 s[2:3], v0, v157
	s_or_b64 vcc, vcc, s[2:3]
	s_cbranch_vccz .LBB0_662
	v_max_f32_e32 v156, v156, v156
	v_max_f32_e32 v157, v187, v187
	v_max_f32_e32 v158, v157, v156
	v_max_f32_e32 v0, v0, v0
	v_max_f32_e32 v156, v186, v186
	v_cmp_ngt_f32_e32 vcc, s76, v158
	v_max_f32_e32 v159, v156, v0
	s_nop 0
	v_cndmask_b32_e32 v0, 0, v158, vcc
	v_sub_f32_e32 v0, v187, v0
	v_mul_f32_e32 v0, 0x3e38aa3b, v0
	v_cmp_ngt_f32_e32 vcc, s76, v159
	v_exp_f32_e32 v157, v0
	v_mov_b32_e32 v187, v158
	v_cndmask_b32_e32 v0, 0, v159, vcc
	v_sub_f32_e32 v0, v186, v0
	v_mul_f32_e32 v0, 0x3e38aa3b, v0
	v_exp_f32_e32 v156, v0
	v_mov_b32_e32 v0, v157
	v_pk_mul_f32 v[64:65], v[64:65], v[0:1] op_sel_hi:[1,0]
	v_pk_mul_f32 v[62:63], v[62:63], v[0:1] op_sel_hi:[1,0]
	v_pk_mul_f32 v[150:151], v[150:151], v[156:157]
	v_pk_mul_f32 v[60:61], v[60:61], v[0:1] op_sel_hi:[1,0]
	v_pk_mul_f32 v[58:59], v[58:59], v[0:1] op_sel_hi:[1,0]
	v_pk_mul_f32 v[56:57], v[56:57], v[0:1] op_sel_hi:[1,0]
	v_pk_mul_f32 v[54:55], v[54:55], v[0:1] op_sel_hi:[1,0]
	v_pk_mul_f32 v[52:53], v[52:53], v[0:1] op_sel_hi:[1,0]
	v_pk_mul_f32 v[50:51], v[50:51], v[0:1] op_sel_hi:[1,0]
	v_pk_mul_f32 v[16:17], v[16:17], v[156:157] op_sel_hi:[1,0]
	v_pk_mul_f32 v[14:15], v[14:15], v[156:157] op_sel_hi:[1,0]
	v_pk_mul_f32 v[12:13], v[12:13], v[156:157] op_sel_hi:[1,0]
	v_pk_mul_f32 v[10:11], v[10:11], v[156:157] op_sel_hi:[1,0]
	v_pk_mul_f32 v[8:9], v[8:9], v[156:157] op_sel_hi:[1,0]
	v_pk_mul_f32 v[6:7], v[6:7], v[156:157] op_sel_hi:[1,0]
	v_pk_mul_f32 v[4:5], v[4:5], v[156:157] op_sel_hi:[1,0]
	v_pk_mul_f32 v[2:3], v[2:3], v[156:157] op_sel_hi:[1,0]
	v_pk_mul_f32 v[48:49], v[48:49], v[0:1] op_sel_hi:[1,0]
	v_pk_mul_f32 v[46:47], v[46:47], v[0:1] op_sel_hi:[1,0]
	v_pk_mul_f32 v[44:45], v[44:45], v[0:1] op_sel_hi:[1,0]
	v_pk_mul_f32 v[42:43], v[42:43], v[0:1] op_sel_hi:[1,0]
	v_pk_mul_f32 v[40:41], v[40:41], v[0:1] op_sel_hi:[1,0]
	v_pk_mul_f32 v[38:39], v[38:39], v[0:1] op_sel_hi:[1,0]
	v_pk_mul_f32 v[36:37], v[36:37], v[0:1] op_sel_hi:[1,0]
	v_pk_mul_f32 v[34:35], v[34:35], v[0:1] op_sel_hi:[1,0]
	v_pk_mul_f32 v[32:33], v[32:33], v[156:157] op_sel_hi:[1,0]
	v_pk_mul_f32 v[30:31], v[30:31], v[156:157] op_sel_hi:[1,0]
	v_pk_mul_f32 v[28:29], v[28:29], v[156:157] op_sel_hi:[1,0]
	v_pk_mul_f32 v[26:27], v[26:27], v[156:157] op_sel_hi:[1,0]
	v_pk_mul_f32 v[24:25], v[24:25], v[156:157] op_sel_hi:[1,0]
	v_pk_mul_f32 v[22:23], v[22:23], v[156:157] op_sel_hi:[1,0]
	v_pk_mul_f32 v[20:21], v[20:21], v[156:157] op_sel_hi:[1,0]
	v_pk_mul_f32 v[18:19], v[18:19], v[156:157] op_sel_hi:[1,0]
	v_mov_b32_e32 v186, v159
.LBB0_662:
	v_mul_f32_e32 v0, 0x3e38aa3b, v187
	v_cmp_ngt_f32_e32 vcc, s76, v187
	v_mul_f32_e32 v156, 0x3e38aa3b, v186
	s_and_b64 s[0:1], s[4:5], exec
	v_cndmask_b32_e32 v0, 0, v0, vcc
	v_fma_f32 v0, -v244, s77, v0
	v_cmp_ngt_f32_e32 vcc, s76, v186
	v_fma_f32 v98, v98, s77, -v0
	v_exp_f32_e32 v157, v98
	v_cndmask_b32_e32 v201, 0, v156, vcc
	v_fma_f32 v201, -v245, s77, v201
	v_fma_f32 v66, v66, s77, -v201
	v_exp_f32_e32 v156, v66
	v_fma_f32 v66, v99, s77, -v0
	v_exp_f32_e32 v99, v66
	v_fma_f32 v66, v115, s77, -v201
	v_fma_f32 v98, v114, s77, -v201
	v_exp_f32_e32 v114, v66
	v_fma_f32 v66, v83, s77, -v0
	v_exp_f32_e32 v115, v66
	v_fma_f32 v66, v67, s77, -v201
	v_exp_f32_e32 v158, v98
	v_exp_f32_e32 v98, v66
	v_fma_f32 v66, v100, s77, -v0
	v_exp_f32_e32 v67, v66
	v_fma_f32 v66, v116, s77, -v201
	v_exp_f32_e32 v160, v66
	v_fma_f32 v66, v84, s77, -v0
	v_exp_f32_e32 v161, v66
	v_fma_f32 v66, v68, s77, -v201
	v_fma_f32 v68, v101, s77, -v0
	v_exp_f32_e32 v83, v68
	v_fma_f32 v68, v117, s77, -v201
	v_exp_f32_e32 v100, v68
	v_fma_f32 v68, v85, s77, -v0
	v_fma_f32 v82, v82, s77, -v0
	v_exp_f32_e32 v101, v68
	v_fma_f32 v68, v69, s77, -v201
	v_exp_f32_e32 v159, v82
	v_exp_f32_e32 v82, v68
	v_fma_f32 v68, v102, s77, -v0
	v_exp_f32_e32 v85, v68
	v_fma_f32 v68, v118, s77, -v201
	v_exp_f32_e32 v116, v68
	v_fma_f32 v68, v86, s77, -v0
	v_exp_f32_e32 v117, v68
	v_fma_f32 v68, v70, s77, -v201
	v_exp_f32_e32 v84, v68
	v_fma_f32 v68, v103, s77, -v0
	v_exp_f32_e32 v69, v68
	v_fma_f32 v68, v119, s77, -v201
	v_exp_f32_e32 v118, v68
	v_fma_f32 v68, v87, s77, -v0
	v_fma_f32 v70, v104, s77, -v0
	v_exp_f32_e32 v119, v68
	v_fma_f32 v68, v71, s77, -v201
	v_exp_f32_e32 v71, v70
	v_fma_f32 v70, v120, s77, -v201
	v_exp_f32_e32 v162, v70
	v_fma_f32 v70, v88, s77, -v0
	v_exp_f32_e32 v163, v70
	v_fma_f32 v70, v72, s77, -v201
	v_fma_f32 v72, v105, s77, -v0
	v_exp_f32_e32 v87, v72
	v_fma_f32 v72, v121, s77, -v201
	v_exp_f32_e32 v120, v72
	v_fma_f32 v72, v89, s77, -v0
	v_exp_f32_e32 v121, v72
	v_fma_f32 v72, v73, s77, -v201
	v_exp_f32_e32 v86, v72
	v_pk_add_f32 v[72:73], v[158:159], 0 op_sel_hi:[1,0]
	s_cselect_b32 s0, s78, 0x7800
	v_pk_add_f32 v[164:165], v[114:115], v[72:73]
	v_fma_f32 v72, v106, s77, -v0
	v_exp_f32_e32 v73, v72
	v_fma_f32 v72, v122, s77, -v201
	v_exp_f32_e32 v88, v72
	v_fma_f32 v72, v107, s77, -v0
	v_exp_f32_e32 v103, v72
	v_fma_f32 v72, v123, s77, -v201
	v_exp_f32_e32 v104, v72
	v_fma_f32 v72, v108, s77, -v0
	v_exp_f32_e32 v107, v72
	v_fma_f32 v72, v124, s77, -v201
	v_exp_f32_e32 v108, v72
	v_add_u32_e32 v216, s0, v179
	v_fma_f32 v72, v109, s77, -v0
	v_cvt_pk_bf16_f32 v188, v157, v99
	v_cvt_pk_bf16_f32 v189, v67, v83
	v_cvt_pk_bf16_f32 v190, v85, v69
	v_cvt_pk_bf16_f32 v191, v71, v87
	v_cvt_pk_bf16_f32 v192, v158, v114
	v_cvt_pk_bf16_f32 v193, v160, v100
	v_cvt_pk_bf16_f32 v194, v116, v118
	v_cvt_pk_bf16_f32 v195, v162, v120
	ds_read_b64_tr_b16 v[196:197], v216
	ds_read_b64_tr_b16 v[198:199], v216 offset:1536
	v_exp_f32_e32 v203, v72
	v_fma_f32 v72, v125, s77, -v201
	ds_read_b64_tr_b16 v[124:125], v216 offset:1600
	ds_read_b64_tr_b16 v[122:123], v216 offset:64
	v_exp_f32_e32 v158, v72
	v_fma_f32 v72, v110, s77, -v0
	v_exp_f32_e32 v205, v72
	v_fma_f32 v72, v126, s77, -v201
	v_exp_f32_e32 v206, v72
	v_fma_f32 v72, v111, s77, -v0
	v_exp_f32_e32 v209, v72
	v_fma_f32 v72, v127, s77, -v201
	v_exp_f32_e32 v210, v72
	v_fma_f32 v72, v112, s77, -v0
	s_waitcnt lgkmcnt(0)
	v_mfma_f32_32x32x16_bf16 v[34:49], v[122:125], v[188:191], v[34:49]
	v_cvt_pk_bf16_f32 v110, v73, v103
	v_cvt_pk_bf16_f32 v111, v107, v203
	v_cvt_pk_bf16_f32 v112, v205, v209
	v_exp_f32_e32 v66, v66
	v_exp_f32_e32 v68, v68
	v_exp_f32_e32 v70, v70
	v_fma_f32 v78, v78, s77, -v201
	v_mfma_f32_32x32x16_bf16 v[18:33], v[122:125], v[192:195], v[18:33]
	v_add_f32_e64 v122, v160, v164
	v_add_f32_e64 v123, v161, v165
	v_exp_f32_e32 v204, v78
	v_pk_add_f32 v[122:123], v[100:101], v[122:123]
	v_fma_f32 v78, v95, s77, -v0
	v_pk_add_f32 v[122:123], v[116:117], v[122:123]
	v_exp_f32_e32 v211, v78
	v_pk_add_f32 v[122:123], v[118:119], v[122:123]
	v_mfma_f32_32x32x16_bf16 v[50:65], v[196:199], v[188:191], v[50:65]
	v_add_f32_e64 v164, v162, v122
	v_add_f32_e64 v165, v163, v123
	v_fma_f32 v78, v79, s77, -v201
	v_exp_f32_e32 v208, v78
	v_fma_f32 v78, v96, s77, -v0
	v_pk_add_f32 v[164:165], v[120:121], v[164:165]
	v_mfma_f32_32x32x16_bf16 v[2:17], v[196:199], v[192:195], v[2:17]
	v_exp_f32_e32 v197, v72
	v_fma_f32 v72, v128, s77, -v201
	v_exp_f32_e32 v198, v72
	v_fma_f32 v72, v113, s77, -v0
	v_exp_f32_e32 v213, v72
	v_fma_f32 v72, v129, s77, -v201
	v_exp_f32_e32 v214, v72
	v_cvt_pk_bf16_f32 v113, v197, v213
	v_cvt_pk_bf16_f32 v126, v88, v104
	v_cvt_pk_bf16_f32 v127, v108, v158
	v_cvt_pk_bf16_f32 v128, v206, v210
	v_cvt_pk_bf16_f32 v129, v198, v214
	ds_read_b64_tr_b16 v[188:189], v216 offset:3072
	ds_read_b64_tr_b16 v[190:191], v216 offset:4608
	ds_read_b64_tr_b16 v[124:125], v216 offset:4672
	ds_read_b64_tr_b16 v[122:123], v216 offset:3136
	v_fma_f32 v72, v90, s77, -v0
	v_exp_f32_e32 v89, v72
	v_fma_f32 v72, v74, s77, -v201
	v_fma_f32 v74, v91, s77, -v0
	v_exp_f32_e32 v105, v74
	v_fma_f32 v74, v75, s77, -v201
	v_exp_f32_e32 v102, v74
	v_fma_f32 v74, v92, s77, -v0
	v_exp_f32_e32 v109, v74
	v_fma_f32 v74, v76, s77, -v201
	v_exp_f32_e32 v106, v74
	v_fma_f32 v74, v93, s77, -v0
	s_waitcnt lgkmcnt(0)
	v_mfma_f32_32x32x16_bf16 v[34:49], v[122:125], v[110:113], v[34:49]
	v_cvt_pk_bf16_f32 v90, v159, v115
	v_exp_f32_e32 v159, v74
	v_fma_f32 v74, v77, s77, -v201
	v_exp_f32_e32 v202, v74
	v_fma_f32 v74, v94, s77, -v0
	v_cvt_pk_bf16_f32 v91, v161, v101
	v_cvt_pk_bf16_f32 v92, v117, v119
	v_mfma_f32_32x32x16_bf16 v[18:33], v[122:125], v[126:129], v[18:33]
	v_cvt_pk_bf16_f32 v93, v163, v121
	v_exp_f32_e32 v207, v74
	v_fma_f32 v0, v97, s77, -v0
	v_exp_f32_e32 v72, v72
	v_exp_f32_e32 v199, v78
	v_fma_f32 v78, v80, s77, -v201
	v_exp_f32_e32 v215, v0
	v_mfma_f32_32x32x16_bf16 v[50:65], v[188:191], v[110:113], v[50:65]
	v_cvt_pk_bf16_f32 v110, v156, v98
	v_cvt_pk_bf16_f32 v111, v66, v82
	v_cvt_pk_bf16_f32 v112, v84, v68
	v_cvt_pk_bf16_f32 v113, v70, v86
	ds_read_b64_tr_b16 v[114:115], v216 offset:6144
	ds_read_b64_tr_b16 v[116:117], v216 offset:7680
	ds_read_b64_tr_b16 v[76:77], v216 offset:7744
	ds_read_b64_tr_b16 v[74:75], v216 offset:6208
	v_fma_f32 v0, v81, s77, -v201
	v_mfma_f32_32x32x16_bf16 v[2:17], v[188:191], v[126:129], v[2:17]
	v_exp_f32_e32 v196, v78
	v_exp_f32_e32 v212, v0
	v_cvt_pk_bf16_f32 v78, v89, v105
	v_cvt_pk_bf16_f32 v79, v109, v159
	v_cvt_pk_bf16_f32 v80, v207, v211
	v_cvt_pk_bf16_f32 v81, v199, v215
	s_waitcnt lgkmcnt(0)
	v_mfma_f32_32x32x16_bf16 v[34:49], v[74:77], v[90:93], v[34:49]
	v_mfma_f32_32x32x16_bf16 v[18:33], v[74:77], v[110:113], v[18:33]
	v_add_f32_e64 v74, v156, 0
	v_add_f32_e64 v75, v157, 0
	v_add_f32_e64 v74, v98, v74
	v_add_f32_e64 v75, v99, v75
	v_add_f32_e64 v66, v66, v74
	v_add_f32_e64 v67, v67, v75
	v_pk_add_f32 v[66:67], v[82:83], v[66:67]
	v_mfma_f32_32x32x16_bf16 v[50:65], v[114:117], v[90:93], v[50:65]
	v_add_f32_e64 v66, v84, v66
	v_add_f32_e64 v67, v85, v67
	v_cvt_pk_bf16_f32 v90, v72, v102
	v_cvt_pk_bf16_f32 v91, v106, v202
	v_cvt_pk_bf16_f32 v92, v204, v208
	v_cvt_pk_bf16_f32 v93, v196, v212
	ds_read_b64_tr_b16 v[94:95], v216 offset:9216
	ds_read_b64_tr_b16 v[96:97], v216 offset:10752
	ds_read_b64_tr_b16 v[76:77], v216 offset:10816
	ds_read_b64_tr_b16 v[74:75], v216 offset:9280
	v_mfma_f32_32x32x16_bf16 v[2:17], v[114:117], v[110:113], v[2:17]
	v_add_f32_e64 v66, v68, v66
	v_add_f32_e64 v67, v69, v67
	v_add_f32_e64 v68, v88, v164
	v_add_f32_e64 v69, v89, v165
	v_add_f32_e64 v66, v70, v66
	v_add_f32_e64 v67, v71, v67
	v_pk_add_f32 v[68:69], v[104:105], v[68:69]
	v_pk_add_f32 v[66:67], v[86:87], v[66:67]
	v_pk_add_f32 v[68:69], v[108:109], v[68:69]
	v_pk_add_f32 v[66:67], v[72:73], v[66:67]
	s_waitcnt lgkmcnt(2)
	v_mfma_f32_32x32x16_bf16 v[50:65], v[94:97], v[78:81], v[50:65]
	v_add_f32_e64 v66, v102, v66
	v_add_f32_e64 v67, v103, v67
	v_add_f32_e64 v68, v158, v68
	v_add_f32_e64 v69, v159, v69
	v_add_f32_e64 v66, v106, v66
	v_add_f32_e64 v67, v107, v67
	v_pk_add_f32 v[68:69], v[206:207], v[68:69]
	v_pk_add_f32 v[66:67], v[202:203], v[66:67]
	v_pk_add_f32 v[68:69], v[210:211], v[68:69]
	v_pk_add_f32 v[66:67], v[204:205], v[66:67]
	v_mfma_f32_32x32x16_bf16 v[2:17], v[94:97], v[90:93], v[2:17]
	v_add_f32_e64 v66, v208, v66
	v_add_f32_e64 v67, v209, v67
	v_add_f32_e64 v68, v198, v68
	v_add_f32_e64 v69, v199, v69
	v_add_f32_e64 v66, v196, v66
	v_add_f32_e64 v67, v197, v67
	v_pk_add_f32 v[68:69], v[214:215], v[68:69]
	v_pk_add_f32 v[66:67], v[212:213], v[66:67]
	s_nop 0
	v_pk_add_f32 v[66:67], v[68:69], v[66:67]
	s_waitcnt lgkmcnt(0)
	v_mfma_f32_32x32x16_bf16 v[34:49], v[74:77], v[78:81], v[34:49]
	v_add_f32_e64 v150, v150, v66
	v_add_f32_e64 v151, v151, v67
	v_mfma_f32_32x32x16_bf16 v[18:33], v[74:77], v[90:93], v[18:33]

.LBB0_1326:
	s_lshr_b32 s0, s0, 2
	s_lshl_b32 s0, 1, s0
	v_and_b32_e32 v64, s0, v205
	v_mov_b32_e32 v168, 0
	v_cmp_ne_u32_e64 s[4:5], 0, v64
	v_cmp_le_i32_e32 vcc, s18, v206
	v_mov_b32_e32 v64, 0
	s_and_saveexec_b64 s[2:3], vcc
	v_cndmask_b32_e64 v64, 0, 1, s[4:5]
	v_cmp_ne_u32_e32 vcc, 0, v64
	s_cmp_lg_u64 vcc, 0
	s_cselect_b64 s[6:7], -1, 0
	v_cndmask_b32_e64 v64, 0, 1, s[6:7]
	s_or_b64 exec, exec, s[2:3]
	v_and_b32_e32 v65, s0, v175
	v_cmp_ne_u32_e32 vcc, 0, v65
	v_cmp_le_i32_e64 s[2:3], s18, v207
	s_and_saveexec_b64 s[6:7], s[2:3]
	v_cndmask_b32_e64 v65, 0, 1, vcc
	v_cmp_ne_u32_e64 s[2:3], 0, v65
	s_cmp_lg_u64 s[2:3], 0
	s_cselect_b64 s[0:1], -1, 0
	v_cndmask_b32_e64 v168, 0, 1, s[0:1]
	s_or_b64 exec, exec, s[6:7]
	v_and_b32_e32 v65, 1, v64
	v_cmp_eq_u32_e64 s[6:7], 1, v65
	v_and_b32_e32 v65, 1, v168
	v_cmp_eq_u32_e64 s[2:3], 1, v65
	s_or_b64 s[0:1], s[6:7], s[2:3]
	s_and_saveexec_b64 s[12:13], s[0:1]
	s_cbranch_execz .LBB0_1338
	v_add_u32_e32 v65, s19, v208
	v_subrev_u32_e32 v66, 63, v65
	v_cmp_gt_i32_e64 s[8:9], s87, v66
	v_cndmask_b32_e64 v215, 0, v202, s[4:5]
	s_cmp_eq_u32 s97, 0
	v_cndmask_b32_e64 v66, 0, v198, s[8:9]
	v_or3_b32 v216, v215, v66, v64
	s_waitcnt lgkmcnt(8)
	v_cndmask_b32_e64 v64, v203, v212, s[4:5]
	v_cndmask_b32_e64 v64, v64, 0, s[8:9]
	s_cselect_b64 s[8:9], -1, 0
	s_and_b64 s[0:1], s[8:9], exec
	s_cselect_b32 s0, 0, 0x2400
	v_subrev_u32_e32 v65, 31, v65
	v_add_u32_e32 v217, s0, v209
	v_cmp_gt_i32_e64 s[4:5], s87, v65
	v_cndmask_b32_e32 v65, v203, v212, vcc
	ds_read_b128 v[186:189], v217 offset:4608
	ds_read_b128 v[190:193], v217
	ds_read_b128 v[194:197], v217 offset:32
	v_cndmask_b32_e64 v65, v65, 0, s[4:5]
	v_cndmask_b32_e64 v252, v203, v64, s[6:7]
	v_cndmask_b32_e64 v253, v203, v65, s[2:3]
	s_waitcnt lgkmcnt(1)
	v_mfma_f32_32x32x16_bf16 v[96:111], v[190:193], v[128:131], 0
	v_mfma_f32_32x32x16_bf16 v[112:127], v[190:193], v[148:151], 0
	v_mfma_f32_32x32x16_bf16 v[80:95], v[186:189], v[128:131], 0
	v_mfma_f32_32x32x16_bf16 v[64:79], v[186:189], v[148:151], 0
	ds_read_b128 v[186:189], v217 offset:4640
	s_waitcnt lgkmcnt(1)
	v_mfma_f32_32x32x16_bf16 v[96:111], v[194:197], v[132:135], v[96:111]
	v_mfma_f32_32x32x16_bf16 v[112:127], v[194:197], v[140:143], v[112:127]
	s_waitcnt lgkmcnt(0)
	v_mfma_f32_32x32x16_bf16 v[80:95], v[186:189], v[132:135], v[80:95]
	v_mfma_f32_32x32x16_bf16 v[64:79], v[186:189], v[140:143], v[64:79]
	ds_read_b128 v[186:189], v217 offset:64
	ds_read_b128 v[190:193], v217 offset:4672
	s_waitcnt lgkmcnt(1)
	v_mfma_f32_32x32x16_bf16 v[96:111], v[186:189], v[136:139], v[96:111]
	v_mfma_f32_32x32x16_bf16 v[112:127], v[186:189], v[144:147], v[112:127]
	s_waitcnt lgkmcnt(0)
	v_mfma_f32_32x32x16_bf16 v[80:95], v[190:193], v[136:139], v[80:95]
	v_mfma_f32_32x32x16_bf16 v[64:79], v[190:193], v[144:147], v[64:79]
	ds_read_b128 v[186:189], v217 offset:96
	ds_read_b128 v[190:193], v217 offset:4704
	s_waitcnt lgkmcnt(1)
	v_mfma_f32_32x32x16_bf16 v[96:111], v[186:189], v[152:155], v[96:111]
	v_mfma_f32_32x32x16_bf16 v[112:127], v[186:189], v[156:159], v[112:127]
	v_cndmask_b32_e64 v186, v215, v216, s[6:7]
	v_and_b32_e32 v187, 0x100, v186
	v_cmp_ne_u32_e64 s[6:7], 0, v187
	s_waitcnt lgkmcnt(0)
	v_mfma_f32_32x32x16_bf16 v[80:95], v[190:193], v[152:155], v[80:95]
	v_mfma_f32_32x32x16_bf16 v[64:79], v[190:193], v[156:159], v[64:79]
	v_add_u32_e32 v190, s19, v211
	s_and_saveexec_b64 s[14:15], s[6:7]
	s_cbranch_execz .LBB0_1333
	v_lshl_add_u32 v224, v190, 2, s91
	v_and_b32_e32 v186, 0x10000, v186
	v_cmp_ne_u32_e64 s[6:7], 0, v186
	v_mov_b32_e32 v225, 0x1d000
	s_nop 1
	v_cndmask_b32_e64 v224, v225, v224, s[6:7]
	ds_read_b32 v226, v224 offset:236
	ds_read_b32 v227, v224 offset:232
	ds_read_b32 v228, v224 offset:228
	ds_read_b32 v229, v224 offset:224
	ds_read_b32 v230, v224 offset:204
	ds_read_b32 v231, v224 offset:200
	ds_read_b32 v232, v224 offset:196
	ds_read_b32 v233, v224 offset:192
	ds_read_b32 v234, v224 offset:172
	ds_read_b32 v235, v224 offset:168
	ds_read_b32 v236, v224 offset:164
	ds_read_b32 v237, v224 offset:160
	ds_read_b32 v238, v224 offset:140
	ds_read_b32 v239, v224 offset:136
	ds_read_b32 v240, v224 offset:132
	ds_read_b32 v241, v224 offset:128
	ds_read_b32 v242, v224 offset:108
	ds_read_b32 v243, v224 offset:104
	ds_read_b32 v244, v224 offset:100
	ds_read_b32 v245, v224 offset:96
	ds_read_b32 v246, v224 offset:76
	ds_read_b32 v247, v224 offset:72
	ds_read_b32 v248, v224 offset:68
	ds_read_b32 v249, v224 offset:64
	ds_read_b32 v250, v224 offset:44
	ds_read_b32 v251, v224 offset:40
	s_waitcnt lgkmcnt(10)
	v_pk_add_f32 v[96:97], v[96:97], v[226:227]
	v_pk_add_f32 v[98:99], v[98:99], v[228:229]
	v_pk_add_f32 v[100:101], v[100:101], v[230:231]
	v_pk_add_f32 v[102:103], v[102:103], v[232:233]
	v_pk_add_f32 v[104:105], v[104:105], v[234:235]
	v_pk_add_f32 v[106:107], v[106:107], v[236:237]
	v_pk_add_f32 v[108:109], v[108:109], v[238:239]
	v_pk_add_f32 v[110:111], v[110:111], v[240:241]
	ds_read_b32 v226, v224 offset:36
	ds_read_b32 v227, v224 offset:32
	ds_read_b32 v228, v224 offset:12
	ds_read_b32 v229, v224 offset:8
	ds_read_b32 v230, v224 offset:4
	ds_read_b32 v231, v224 offset:0
	s_waitcnt lgkmcnt(6)
	v_pk_add_f32 v[80:81], v[80:81], v[242:243]
	v_pk_add_f32 v[82:83], v[82:83], v[244:245]
	v_pk_add_f32 v[84:85], v[84:85], v[246:247]
	v_pk_add_f32 v[86:87], v[86:87], v[248:249]
	v_pk_add_f32 v[88:89], v[88:89], v[250:251]
	s_waitcnt lgkmcnt(0)
	v_pk_add_f32 v[90:91], v[90:91], v[226:227]
	v_pk_add_f32 v[92:93], v[92:93], v[228:229]
	v_pk_add_f32 v[94:95], v[94:95], v[230:231]
.LBB0_1333:
	s_or_b64 exec, exec, s[14:15]
	v_cndmask_b32_e32 v186, 0, v202, vcc
	v_cndmask_b32_e64 v187, 0, v198, s[4:5]
	v_or3_b32 v168, v186, v187, v168
	v_cndmask_b32_e64 v168, v186, v168, s[2:3]
	v_and_b32_e32 v186, 0x100, v168
	v_cmp_ne_u32_e32 vcc, 0, v186
	s_and_saveexec_b64 s[2:3], vcc
	s_cbranch_execz .LBB0_1335
	v_lshl_add_u32 v224, v190, 2, s32
	v_and_b32_e32 v187, 0x10000, v168
	v_cmp_ne_u32_e32 vcc, 0, v187
	v_mov_b32_e32 v225, 0x1d000
	s_nop 1
	v_cndmask_b32_e32 v224, v225, v224, vcc
	ds_read_b32 v226, v224 offset:236
	ds_read_b32 v227, v224 offset:232
	ds_read_b32 v228, v224 offset:228
	ds_read_b32 v229, v224 offset:224
	ds_read_b32 v230, v224 offset:204
	ds_read_b32 v231, v224 offset:200
	ds_read_b32 v232, v224 offset:196
	ds_read_b32 v233, v224 offset:192
	ds_read_b32 v234, v224 offset:172
	ds_read_b32 v235, v224 offset:168
	ds_read_b32 v236, v224 offset:164
	ds_read_b32 v237, v224 offset:160
	ds_read_b32 v238, v224 offset:140
	ds_read_b32 v239, v224 offset:136
	ds_read_b32 v240, v224 offset:132
	ds_read_b32 v241, v224 offset:128
	ds_read_b32 v242, v224 offset:108
	ds_read_b32 v243, v224 offset:104
	ds_read_b32 v244, v224 offset:100
	ds_read_b32 v245, v224 offset:96
	ds_read_b32 v246, v224 offset:76
	ds_read_b32 v247, v224 offset:72
	ds_read_b32 v248, v224 offset:68
	ds_read_b32 v249, v224 offset:64
	ds_read_b32 v250, v224 offset:44
	ds_read_b32 v251, v224 offset:40
	s_waitcnt lgkmcnt(10)
	v_pk_add_f32 v[112:113], v[112:113], v[226:227]
	v_pk_add_f32 v[114:115], v[114:115], v[228:229]
	v_pk_add_f32 v[116:117], v[116:117], v[230:231]
	v_pk_add_f32 v[118:119], v[118:119], v[232:233]
	v_pk_add_f32 v[120:121], v[120:121], v[234:235]
	v_pk_add_f32 v[122:123], v[122:123], v[236:237]
	v_pk_add_f32 v[124:125], v[124:125], v[238:239]
	v_pk_add_f32 v[126:127], v[126:127], v[240:241]
	ds_read_b32 v226, v224 offset:36
	ds_read_b32 v227, v224 offset:32
	ds_read_b32 v228, v224 offset:12
	ds_read_b32 v229, v224 offset:8
	ds_read_b32 v230, v224 offset:4
	ds_read_b32 v231, v224 offset:0
	s_waitcnt lgkmcnt(6)
	v_pk_add_f32 v[64:65], v[64:65], v[242:243]
	v_pk_add_f32 v[66:67], v[66:67], v[244:245]
	v_pk_add_f32 v[68:69], v[68:69], v[246:247]
	v_pk_add_f32 v[70:71], v[70:71], v[248:249]
	v_pk_add_f32 v[72:73], v[72:73], v[250:251]
	s_waitcnt lgkmcnt(0)
	v_pk_add_f32 v[74:75], v[74:75], v[226:227]
	v_pk_add_f32 v[76:77], v[76:77], v[228:229]
	v_pk_add_f32 v[78:79], v[78:79], v[230:231]
.LBB0_1335:
	s_or_b64 exec, exec, s[2:3]
	v_max_f32_e32 v168, v96, v80
	v_max_f32_e32 v186, v97, v81
	v_max_f32_e32 v187, v99, v83
	v_max3_f32 v188, v98, v82, v102
	v_max3_f32 v187, v187, v103, v87
	v_max3_f32 v168, v168, v100, v84
	v_max3_f32 v186, v186, v101, v85
	v_max3_f32 v188, v188, v86, v106
	v_max3_f32 v187, v187, v107, v91
	v_max3_f32 v168, v168, v104, v88
	v_max3_f32 v186, v186, v105, v89
	v_max3_f32 v188, v188, v90, v110
	v_max3_f32 v187, v187, v111, v95
	v_max3_f32 v168, v168, v108, v92
	v_max3_f32 v186, v186, v109, v93
	v_max3_f32 v187, v188, v94, v187
	v_max3_f32 v168, v168, v186, v187
	v_max_f32_e32 v186, v112, v64
	v_max_f32_e32 v187, v113, v65
	v_max_f32_e32 v188, v115, v67
	v_max3_f32 v189, v114, v66, v118
	v_max3_f32 v188, v188, v119, v71
	v_max3_f32 v186, v186, v116, v68
	v_max3_f32 v187, v187, v117, v69
	v_max3_f32 v189, v189, v70, v122
	v_max3_f32 v188, v188, v123, v75
	v_max3_f32 v186, v186, v120, v72
	v_max3_f32 v187, v187, v121, v73
	v_max3_f32 v189, v189, v74, v126
	v_max3_f32 v188, v188, v127, v79
	v_max3_f32 v186, v186, v124, v76
	v_max3_f32 v187, v187, v125, v77
	v_max3_f32 v188, v189, v78, v188
	v_max3_f32 v187, v186, v187, v188
	v_mov_b32_e32 v189, v168
	v_mov_b32_e32 v188, v187
	s_nop 1
	v_permlane32_swap_b32_e32 v168, v189
	v_permlane32_swap_b32_e32 v187, v188
	v_max_f32_e32 v186, v168, v189
	v_max_f32_e32 v168, v187, v188
	v_add_f32_e32 v186, v186, v252
	v_add_f32_e32 v168, v168, v253
	v_add_f32_e32 v187, 0x42317218, v214
	v_cmp_gt_f32_e32 vcc, v186, v187
	v_add_f32_e32 v187, 0x42317218, v213
	v_cmp_gt_f32_e64 s[2:3], v168, v187
	s_or_b64 vcc, vcc, s[2:3]
	s_cbranch_vccz .LBB0_1337
	v_max_f32_e32 v186, v186, v186
	v_max_f32_e32 v187, v214, v214
	v_max_f32_e32 v188, v187, v186
	v_max_f32_e32 v168, v168, v168
	v_max_f32_e32 v186, v213, v213
	v_cmp_ngt_f32_e32 vcc, s88, v188
	v_max_f32_e32 v189, v186, v168
	s_nop 0
	v_cndmask_b32_e32 v168, 0, v188, vcc
	v_sub_f32_e32 v168, v214, v168
	v_mul_f32_e32 v168, 0x3e38aa3b, v168
	v_cmp_ngt_f32_e32 vcc, s88, v189
	v_exp_f32_e32 v187, v168
	v_mov_b32_e32 v214, v188
	v_cndmask_b32_e32 v168, 0, v189, vcc
	v_sub_f32_e32 v168, v213, v168
	v_mul_f32_e32 v168, 0x3e38aa3b, v168
	v_exp_f32_e32 v186, v168
	v_mov_b32_e32 v168, v187
	v_pk_mul_f32 v[62:63], v[62:63], v[168:169] op_sel_hi:[1,0]
	v_pk_mul_f32 v[60:61], v[60:61], v[168:169] op_sel_hi:[1,0]
	v_pk_mul_f32 v[178:179], v[178:179], v[186:187]
	v_pk_mul_f32 v[58:59], v[58:59], v[168:169] op_sel_hi:[1,0]
	v_pk_mul_f32 v[56:57], v[56:57], v[168:169] op_sel_hi:[1,0]
	v_pk_mul_f32 v[54:55], v[54:55], v[168:169] op_sel_hi:[1,0]
	v_pk_mul_f32 v[52:53], v[52:53], v[168:169] op_sel_hi:[1,0]
	v_pk_mul_f32 v[50:51], v[50:51], v[168:169] op_sel_hi:[1,0]
	v_pk_mul_f32 v[48:49], v[48:49], v[168:169] op_sel_hi:[1,0]
	v_pk_mul_f32 v[14:15], v[14:15], v[186:187] op_sel_hi:[1,0]
	v_pk_mul_f32 v[12:13], v[12:13], v[186:187] op_sel_hi:[1,0]
	v_pk_mul_f32 v[10:11], v[10:11], v[186:187] op_sel_hi:[1,0]
	v_pk_mul_f32 v[8:9], v[8:9], v[186:187] op_sel_hi:[1,0]
	v_pk_mul_f32 v[6:7], v[6:7], v[186:187] op_sel_hi:[1,0]
	v_pk_mul_f32 v[4:5], v[4:5], v[186:187] op_sel_hi:[1,0]
	v_pk_mul_f32 v[2:3], v[2:3], v[186:187] op_sel_hi:[1,0]
	v_pk_mul_f32 v[0:1], v[0:1], v[186:187] op_sel_hi:[1,0]
	v_pk_mul_f32 v[46:47], v[46:47], v[168:169] op_sel_hi:[1,0]
	v_pk_mul_f32 v[44:45], v[44:45], v[168:169] op_sel_hi:[1,0]
	v_pk_mul_f32 v[42:43], v[42:43], v[168:169] op_sel_hi:[1,0]
	v_pk_mul_f32 v[40:41], v[40:41], v[168:169] op_sel_hi:[1,0]
	v_pk_mul_f32 v[38:39], v[38:39], v[168:169] op_sel_hi:[1,0]
	v_pk_mul_f32 v[36:37], v[36:37], v[168:169] op_sel_hi:[1,0]
	v_pk_mul_f32 v[34:35], v[34:35], v[168:169] op_sel_hi:[1,0]
	v_pk_mul_f32 v[32:33], v[32:33], v[168:169] op_sel_hi:[1,0]
	v_pk_mul_f32 v[30:31], v[30:31], v[186:187] op_sel_hi:[1,0]
	v_pk_mul_f32 v[28:29], v[28:29], v[186:187] op_sel_hi:[1,0]
	v_pk_mul_f32 v[26:27], v[26:27], v[186:187] op_sel_hi:[1,0]
	v_pk_mul_f32 v[24:25], v[24:25], v[186:187] op_sel_hi:[1,0]
	v_pk_mul_f32 v[22:23], v[22:23], v[186:187] op_sel_hi:[1,0]
	v_pk_mul_f32 v[20:21], v[20:21], v[186:187] op_sel_hi:[1,0]
	v_pk_mul_f32 v[18:19], v[18:19], v[186:187] op_sel_hi:[1,0]
	v_pk_mul_f32 v[16:17], v[16:17], v[186:187] op_sel_hi:[1,0]
	v_mov_b32_e32 v213, v189
.LBB0_1337:
	v_mul_f32_e32 v168, 0x3e38aa3b, v214
	v_cmp_ngt_f32_e32 vcc, s88, v214
	v_mul_f32_e32 v186, 0x3e38aa3b, v213
	s_and_b64 s[0:1], s[8:9], exec
	v_cndmask_b32_e32 v168, 0, v168, vcc
	v_fma_f32 v168, -v252, s89, v168
	v_cmp_ngt_f32_e32 vcc, s88, v213
	v_fma_f32 v96, v96, s89, -v168
	v_exp_f32_e32 v187, v96
	v_cndmask_b32_e32 v215, 0, v186, vcc
	v_fma_f32 v215, -v253, s89, v215
	v_fma_f32 v64, v64, s89, -v215
	v_exp_f32_e32 v186, v64
	v_fma_f32 v64, v97, s89, -v168
	v_exp_f32_e32 v97, v64
	v_fma_f32 v64, v113, s89, -v215
	v_fma_f32 v96, v112, s89, -v215
	v_exp_f32_e32 v112, v64
	v_fma_f32 v64, v81, s89, -v168
	v_exp_f32_e32 v113, v64
	v_fma_f32 v64, v65, s89, -v215
	v_exp_f32_e32 v188, v96
	v_exp_f32_e32 v96, v64
	v_fma_f32 v64, v98, s89, -v168
	v_exp_f32_e32 v65, v64
	v_fma_f32 v64, v114, s89, -v215
	v_exp_f32_e32 v190, v64
	v_fma_f32 v64, v82, s89, -v168
	v_exp_f32_e32 v191, v64
	v_fma_f32 v64, v66, s89, -v215
	v_fma_f32 v66, v99, s89, -v168
	v_exp_f32_e32 v81, v66
	v_fma_f32 v66, v115, s89, -v215
	v_exp_f32_e32 v98, v66
	v_fma_f32 v66, v83, s89, -v168
	v_fma_f32 v80, v80, s89, -v168
	v_exp_f32_e32 v99, v66
	v_fma_f32 v66, v67, s89, -v215
	v_exp_f32_e32 v189, v80
	v_exp_f32_e32 v80, v66
	v_fma_f32 v66, v100, s89, -v168
	v_exp_f32_e32 v67, v66
	v_fma_f32 v66, v116, s89, -v215
	v_exp_f32_e32 v114, v66
	v_fma_f32 v66, v84, s89, -v168
	v_exp_f32_e32 v115, v66
	v_fma_f32 v66, v68, s89, -v215
	v_fma_f32 v68, v101, s89, -v168
	v_exp_f32_e32 v83, v68
	v_fma_f32 v68, v117, s89, -v215
	v_exp_f32_e32 v192, v68
	v_fma_f32 v68, v85, s89, -v168
	v_pk_add_f32 v[84:85], v[188:189], 0 op_sel_hi:[1,0]
	v_exp_f32_e32 v193, v68
	v_fma_f32 v68, v69, s89, -v215
	v_pk_add_f32 v[84:85], v[112:113], v[84:85]
	v_exp_f32_e32 v82, v68
	v_fma_f32 v68, v102, s89, -v168
	v_pk_add_f32 v[84:85], v[190:191], v[84:85]
	v_exp_f32_e32 v69, v68
	v_fma_f32 v68, v118, s89, -v215
	v_pk_add_f32 v[84:85], v[98:99], v[84:85]
	v_exp_f32_e32 v194, v68
	v_fma_f32 v68, v86, s89, -v168
	v_pk_add_f32 v[84:85], v[114:115], v[84:85]
	v_exp_f32_e32 v195, v68
	v_fma_f32 v68, v70, s89, -v215
	v_pk_add_f32 v[196:197], v[192:193], v[84:85]
	v_fma_f32 v70, v103, s89, -v168
	v_fma_f32 v84, v105, s89, -v168
	v_exp_f32_e32 v85, v70
	v_fma_f32 v70, v119, s89, -v215
	v_exp_f32_e32 v103, v84
	v_fma_f32 v84, v121, s89, -v215
	v_exp_f32_e32 v86, v70
	v_fma_f32 v70, v104, s89, -v168
	v_exp_f32_e32 v104, v84
	v_fma_f32 v84, v106, s89, -v168
	v_exp_f32_e32 v117, v84
	v_fma_f32 v84, v122, s89, -v215
	s_cselect_b32 s0, s92, 0x7800
	v_exp_f32_e32 v106, v84
	v_fma_f32 v84, v107, s89, -v168
	v_add_u32_e32 v234, s0, v185
	v_exp_f32_e32 v229, v84
	v_fma_f32 v84, v123, s89, -v215
	v_exp_f32_e32 v101, v70
	v_fma_f32 v70, v120, s89, -v215
	v_cvt_pk_bf16_f32 v118, v187, v97
	v_cvt_pk_bf16_f32 v119, v65, v81
	v_cvt_pk_bf16_f32 v120, v67, v83
	v_cvt_pk_bf16_f32 v121, v69, v85
	v_cvt_pk_bf16_f32 v216, v188, v112
	v_cvt_pk_bf16_f32 v217, v190, v98
	v_cvt_pk_bf16_f32 v218, v114, v192
	v_cvt_pk_bf16_f32 v219, v194, v86
	ds_read_b64_tr_b16 v[220:221], v234
	ds_read_b64_tr_b16 v[222:223], v234 offset:1536
	v_exp_f32_e32 v98, v84
	v_fma_f32 v84, v108, s89, -v168
	ds_read_b64_tr_b16 v[226:227], v234 offset:1600
	ds_read_b64_tr_b16 v[224:225], v234 offset:64
	v_exp_f32_e32 v231, v84
	v_fma_f32 v84, v124, s89, -v215
	v_exp_f32_e32 v188, v84
	v_fma_f32 v84, v109, s89, -v168
	v_exp_f32_e32 v233, v84
	v_fma_f32 v84, v125, s89, -v215
	v_exp_f32_e32 v190, v84
	v_fma_f32 v84, v110, s89, -v168
	s_waitcnt lgkmcnt(2)
	v_mfma_f32_32x32x16_bf16 v[48:63], v[220:223], v[118:121], v[48:63]
	v_exp_f32_e32 v70, v70
	v_cvt_pk_bf16_f32 v108, v101, v103
	v_cvt_pk_bf16_f32 v109, v117, v229
	v_cvt_pk_bf16_f32 v110, v231, v233
	v_fma_f32 v72, v72, s89, -v215
	v_exp_f32_e32 v100, v72
	v_fma_f32 v72, v89, s89, -v168
	v_mfma_f32_32x32x16_bf16 v[0:15], v[220:223], v[216:219], v[0:15]
	v_exp_f32_e32 v221, v84
	v_fma_f32 v84, v126, s89, -v215
	v_exp_f32_e32 v126, v84
	v_fma_f32 v84, v111, s89, -v168
	v_exp_f32_e32 v223, v84
	v_fma_f32 v84, v127, s89, -v215
	v_exp_f32_e32 v192, v84
	s_waitcnt lgkmcnt(0)
	v_mfma_f32_32x32x16_bf16 v[32:47], v[224:227], v[118:121], v[32:47]
	v_cvt_pk_bf16_f32 v111, v221, v223
	v_cvt_pk_bf16_f32 v118, v70, v104
	v_cvt_pk_bf16_f32 v119, v106, v98
	v_cvt_pk_bf16_f32 v120, v188, v190
	v_cvt_pk_bf16_f32 v121, v126, v192
	ds_read_b64_tr_b16 v[122:123], v234 offset:3072
	ds_read_b64_tr_b16 v[124:125], v234 offset:4608
	v_exp_f32_e32 v105, v72
	v_mfma_f32_32x32x16_bf16 v[16:31], v[224:227], v[216:219], v[16:31]
	ds_read_b64_tr_b16 v[218:219], v234 offset:4672
	ds_read_b64_tr_b16 v[216:217], v234 offset:3136
	v_fma_f32 v72, v73, s89, -v215
	v_exp_f32_e32 v102, v72
	v_fma_f32 v72, v90, s89, -v168
	v_exp_f32_e32 v107, v72
	v_fma_f32 v72, v74, s89, -v215
	v_fma_f32 v84, v87, s89, -v168
	v_fma_f32 v71, v71, s89, -v215
	v_exp_f32_e32 v116, v72
	v_fma_f32 v72, v91, s89, -v168
	s_waitcnt lgkmcnt(0)
	v_mfma_f32_32x32x16_bf16 v[32:47], v[216:219], v[108:111], v[32:47]
	v_exp_f32_e32 v87, v84
	v_exp_f32_e32 v84, v71
	v_fma_f32 v71, v88, s89, -v168
	v_cvt_pk_bf16_f32 v88, v189, v113
	v_cvt_pk_bf16_f32 v89, v191, v99
	v_exp_f32_e32 v99, v72
	v_fma_f32 v72, v75, s89, -v215
	v_mfma_f32_32x32x16_bf16 v[16:31], v[216:219], v[118:121], v[16:31]
	v_exp_f32_e32 v228, v72
	v_fma_f32 v72, v92, s89, -v168
	v_exp_f32_e32 v64, v64
	v_exp_f32_e32 v66, v66
	v_exp_f32_e32 v68, v68
	v_cvt_pk_bf16_f32 v90, v115, v193
	v_cvt_pk_bf16_f32 v91, v195, v87
	v_mfma_f32_32x32x16_bf16 v[48:63], v[122:125], v[108:111], v[48:63]
	v_cvt_pk_bf16_f32 v108, v186, v96
	v_cvt_pk_bf16_f32 v109, v64, v80
	v_cvt_pk_bf16_f32 v110, v66, v82
	v_cvt_pk_bf16_f32 v111, v68, v84
	ds_read_b64_tr_b16 v[112:113], v234 offset:6144
	ds_read_b64_tr_b16 v[114:115], v234 offset:7680
	v_exp_f32_e32 v189, v72
	ds_read_b64_tr_b16 v[74:75], v234 offset:7744
	ds_read_b64_tr_b16 v[72:73], v234 offset:6208
	v_mfma_f32_32x32x16_bf16 v[0:15], v[122:125], v[118:121], v[0:15]
	v_fma_f32 v76, v76, s89, -v215
	v_exp_f32_e32 v230, v76
	v_fma_f32 v76, v93, s89, -v168
	v_pk_add_f32 v[224:225], v[186:187], 0 op_sel_hi:[1,0]
	v_exp_f32_e32 v191, v76
	v_fma_f32 v76, v77, s89, -v215
	v_exp_f32_e32 v232, v76
	v_fma_f32 v76, v94, s89, -v168
	s_waitcnt lgkmcnt(0)
	v_mfma_f32_32x32x16_bf16 v[32:47], v[72:75], v[88:91], v[32:47]
	v_exp_f32_e32 v127, v76
	v_fma_f32 v76, v78, s89, -v215
	v_exp_f32_e32 v220, v76
	v_fma_f32 v76, v95, s89, -v168
	v_exp_f32_e32 v71, v71
	v_exp_f32_e32 v193, v76
	v_fma_f32 v76, v79, s89, -v215
	v_mfma_f32_32x32x16_bf16 v[16:31], v[72:75], v[108:111], v[16:31]
	v_add_f32_e64 v72, v96, v224
	v_add_f32_e64 v73, v97, v225
	v_exp_f32_e32 v222, v76
	v_pk_add_f32 v[64:65], v[64:65], v[72:73]
	v_cvt_pk_bf16_f32 v76, v71, v105
	v_cvt_pk_bf16_f32 v77, v107, v99
	v_cvt_pk_bf16_f32 v78, v189, v191
	v_cvt_pk_bf16_f32 v79, v127, v193
	v_mfma_f32_32x32x16_bf16 v[48:63], v[112:115], v[88:91], v[48:63]
	v_add_f32_e64 v64, v80, v64
	v_add_f32_e64 v65, v81, v65
	v_cvt_pk_bf16_f32 v88, v100, v102
	v_cvt_pk_bf16_f32 v89, v116, v228
	v_cvt_pk_bf16_f32 v90, v230, v232
	v_cvt_pk_bf16_f32 v91, v220, v222
	ds_read_b64_tr_b16 v[92:93], v234 offset:9216
	ds_read_b64_tr_b16 v[94:95], v234 offset:10752
	v_add_f32_e64 v64, v66, v64
	v_add_f32_e64 v65, v67, v65
	v_mfma_f32_32x32x16_bf16 v[0:15], v[112:115], v[108:111], v[0:15]
	v_add_f32_e64 v72, v82, v64
	v_add_f32_e64 v73, v83, v65
	ds_read_b64_tr_b16 v[66:67], v234 offset:10816
	ds_read_b64_tr_b16 v[64:65], v234 offset:9280
	v_add_f32_e64 v196, v194, v196
	v_add_f32_e64 v197, v195, v197
	v_pk_add_f32 v[68:69], v[68:69], v[72:73]
	v_pk_add_f32 v[72:73], v[86:87], v[196:197]
	v_pk_add_f32 v[68:69], v[84:85], v[68:69]
	v_pk_add_f32 v[70:71], v[70:71], v[72:73]
	v_pk_add_f32 v[68:69], v[100:101], v[68:69]
	v_pk_add_f32 v[70:71], v[104:105], v[70:71]
	v_pk_add_f32 v[68:69], v[102:103], v[68:69]
	s_waitcnt lgkmcnt(2)
	v_mfma_f32_32x32x16_bf16 v[48:63], v[92:95], v[76:79], v[48:63]
	v_add_f32_e64 v70, v106, v70
	v_add_f32_e64 v71, v107, v71
	v_add_f32_e64 v68, v116, v68
	v_add_f32_e64 v69, v117, v69
	v_add_f32_e64 v70, v98, v70
	v_add_f32_e64 v71, v99, v71
	v_pk_add_f32 v[68:69], v[228:229], v[68:69]
	v_pk_add_f32 v[70:71], v[188:189], v[70:71]
	v_pk_add_f32 v[68:69], v[230:231], v[68:69]
	v_pk_add_f32 v[70:71], v[190:191], v[70:71]
	v_mfma_f32_32x32x16_bf16 v[0:15], v[92:95], v[88:91], v[0:15]
	v_add_f32_e64 v68, v232, v68
	v_add_f32_e64 v69, v233, v69
	v_add_f32_e64 v70, v126, v70
	v_add_f32_e64 v71, v127, v71
	v_add_f32_e64 v68, v220, v68
	v_add_f32_e64 v69, v221, v69
	v_pk_add_f32 v[70:71], v[192:193], v[70:71]
	v_pk_add_f32 v[68:69], v[222:223], v[68:69]
	s_nop 0
	v_pk_add_f32 v[68:69], v[70:71], v[68:69]
	s_waitcnt lgkmcnt(0)
	v_mfma_f32_32x32x16_bf16 v[32:47], v[64:67], v[76:79], v[32:47]
	v_add_f32_e64 v178, v178, v68
	v_add_f32_e64 v179, v179, v69
	v_mfma_f32_32x32x16_bf16 v[16:31], v[64:67], v[88:91], v[16:31]
